# c15 + rg_fused item mapping: channel block rotated by run index ((it + it/8) & 7) so one XCD covers all 8 column blocks
# baseline (speedup 1.0000x reference)
; __device__ __forceinline__ void p_rg_fused(const Frame& F0, const bf16* URAW, int L, const float* cw, const float* cbias, const bf16* Wg, const float* ba, const float* bx, const float* spt,
;                                            bf16* LA, bf16* INP, float* HEND, float* PROD) {
;     ...
;     for (int it = blockIdx.x; it < 64 * 8; it += F.G) {
;         const int nb = it & 7, run = it >> 3, t0 = run * 128;
;         { const int co = F.tid & 31, tq = F.tid >> 5, c0 = nb * 256 + co * 8, tb = t0 + 8 * tq, tl = tb % L;
;           float w[4][8], bias[8];
; #pragma unroll
;           for (int k = 0; k < 4; ++k) { const f32x4 a = *(const f32x4*)(cw + (size_t)k * D + c0), b = *(const f32x4*)(cw + (size_t)k * D + c0 + 4);
;               w[k][0] = a.x; w[k][1] = a.y; w[k][2] = a.z; w[k][3] = a.w; w[k][4] = b.x; w[k][5] = b.y; w[k][6] = b.z; w[k][7] = b.w; }
;           { const f32x4 a = *(const f32x4*)(cbias + c0), b = *(const f32x4*)(cbias + c0 + 4); bias[0] = a.x; bias[1] = a.y; bias[2] = a.z; bias[3] = a.w; bias[4] = b.x; bias[5] = b.y; bias[6] = b.z; bias[7] = b.w; }
;           u32x4 rows[11];
; #pragma unroll
;           for (int i = 0; i < 11; ++i) { const int tt = tl - 1 + i; const bool ok = (tt >= 0) && (tt < L);
;               rows[i] = ok ? *(const u32x4*)(URAW + (size_t)(tb - 1 + i) * D + c0) : (u32x4){0u, 0u, 0u, 0u}; }
.LBB0_832:
	s_lshr_b32 s2, s56, 3
	s_add_i32 s2, s2, s56
	s_and_b32 s2, s2, 7
	s_lshl_b32 s57, s2, 8
	v_or_b32_e32 v43, s57, v160
	v_lshlrev_b32_e32 v130, 2, v43
	v_lshl_add_u64 v[18:19], s[44:45], 0, v[130:131]
	v_add_co_u32_e32 v8, vcc, 0x2000, v18
	s_mov_b64 s[0:1], 0x2000
	s_nop 0
	v_addc_co_u32_e32 v9, vcc, 0, v19, vcc
	v_lshl_add_u64 v[6:7], v[18:19], 0, s[0:1]
	s_mov_b64 s[0:1], 0x4000
	v_add_co_u32_e32 v16, vcc, 0x4000, v18
	v_lshl_add_u64 v[14:15], v[18:19], 0, s[0:1]
	s_nop 0
	v_addc_co_u32_e32 v17, vcc, 0, v19, vcc
	s_mov_b64 s[0:1], 0x6000
	v_lshl_add_u64 v[20:21], v[18:19], 0, s[0:1]
	v_add_co_u32_e32 v18, vcc, 0x6000, v18
	global_load_dwordx4 v[2:5], v130, s[44:45] offset:16
	global_load_dwordx4 v[10:13], v130, s[44:45]
	v_addc_co_u32_e32 v19, vcc, 0, v19, vcc
	global_load_dwordx4 v[22:25], v[8:9], off
	s_nop 0
	global_load_dwordx4 v[6:9], v[6:7], off offset:16
	s_nop 0
	global_load_dwordx4 v[26:29], v[16:17], off
	s_nop 0
	global_load_dwordx4 v[14:17], v[14:15], off offset:16
	s_nop 0
	global_load_dwordx4 v[30:33], v[18:19], off
	s_nop 0
	global_load_dwordx4 v[18:21], v[20:21], off offset:16
	s_nop 0
	global_load_dwordx4 v[34:37], v130, s[46:47] offset:16
	global_load_dwordx4 v[38:41], v130, s[46:47]
	s_ashr_i32 s10, s56, 3
	s_lshl_b32 s16, s10, 7
	v_add_u32_e32 v86, s16, v161
	v_sub_u32_e32 v44, 0, v86
	v_max_i32_e32 v44, v86, v44
	v_mul_hi_u32 v45, v44, v235
	v_mul_lo_u32 v45, v45, s88
	v_sub_u32_e32 v44, v44, v45
	v_subrev_u32_e32 v45, s88, v44
	v_cmp_le_u32_e32 vcc, s88, v44
	v_ashrrev_i32_e32 v87, 31, v86
	v_lshlrev_b32_e32 v130, 1, v43
	v_cndmask_b32_e32 v44, v44, v45, vcc
	v_subrev_u32_e32 v45, s88, v44
	v_cmp_le_u32_e32 vcc, s88, v44
	v_mov_b32_e32 v42, 0
	v_lshl_add_u64 v[88:89], s[12:13], 0, v[130:131]
	v_cndmask_b32_e32 v44, v44, v45, vcc
	v_xor_b32_e32 v44, v44, v87
	v_sub_u32_e32 v62, v44, v87
	v_add_u32_e32 v44, -1, v62
	v_cmp_gt_u32_e32 vcc, s88, v44
	s_waitcnt vmcnt(0)
	v_mov_b32_e32 v50, 0
	v_mov_b32_e32 v51, 0
	v_mov_b32_e32 v52, 0
	v_mov_b32_e32 v53, 0
	s_and_saveexec_b64 s[18:19], vcc
	s_cbranch_execz .LBB0_834
	v_lshlrev_b64 v[44:45], 12, v[86:87]
	v_lshl_add_u64 v[44:45], v[88:89], 0, v[44:45]
	global_load_dwordx4 v[50:53], v[44:45], off offset:-4096
